# grid barriers: L1 invalidate issued right behind the arrival atomic (awaited with vmcnt(1)) so it overlaps the leader's L2 write-back
# speedup vs baseline: 1.0009x; 1.0009x over previous
; __device__ __forceinline__ unsigned xb_ld(unsigned* p)              { return __hip_atomic_load(p, __ATOMIC_RELAXED, __HIP_MEMORY_SCOPE_AGENT); }
; __device__ __forceinline__ unsigned xb_add(unsigned* p, unsigned v) { return __hip_atomic_fetch_add(p, v, __ATOMIC_RELAXED, __HIP_MEMORY_SCOPE_AGENT); }
; #define XB_SPIN(cond, bar) do { unsigned _sp = 0; while (cond) { __builtin_amdgcn_s_sleep(1); \
;     if ((++_sp & 255u) == 0u) { if (xb_ld(&(bar)[XB_TMO])) break; if (_sp > XB_SPIN_CAP) { atomicAdd(&(bar)[XB_TMO], 1u); break; } } } } while (0)
; __device__ __forceinline__ void xcd_barrier(const XcdBarrier& b) {
;     ...
;         const unsigned old = xb_add(&bar[XB_XSUB(b.x)], 1u);
;         const unsigned gen = old / nloc;
;         if (old + 1u == (gen + 1u) * nloc) {
;             __builtin_amdgcn_fence(__ATOMIC_RELEASE, "agent");
;             asm volatile("s_waitcnt vmcnt(0)" ::: "memory");
;             const unsigned og = xb_add(&bar[XB_TOP], 1u);
;             const unsigned tg = og / nx;
;             if (og + 1u == (tg + 1u) * nx) xb_add(&bar[XB_TOPGEN], 1u);
;             else XB_SPIN(xb_ld(&bar[XB_TOPGEN]) == tg, bar);
;             __builtin_amdgcn_fence(__ATOMIC_ACQUIRE, "agent");
;             xb_add(&bar[XB_XGEN(b.x)], 1u);
;             asm volatile("s_waitcnt vmcnt(0)" ::: "memory");
;         } else {
;             XB_SPIN(xb_ld(&bar[XB_XGEN(b.x)]) == gen, bar);
;             __builtin_amdgcn_fence(__ATOMIC_ACQUIRE, "agent");
.LBB0_149:
	s_or_b64 exec, exec, s[10:11]
	buffer_inv sc1
	v_cvt_f32_u32_e32 v4, v2
	s_waitcnt vmcnt(1)
	v_readfirstlane_b32 s8, v3
	v_sub_u32_e32 v3, 0, v2
	v_rcp_iflag_f32_e32 v4, v4
	v_add_u32_e32 v5, s8, v1
	v_mul_f32_e32 v4, 0x4f7ffffe, v4
	v_cvt_u32_f32_e32 v4, v4
	v_mul_lo_u32 v1, v3, v4
	v_mul_hi_u32 v1, v4, v1
	v_add_u32_e32 v1, v4, v1
	v_mul_hi_u32 v1, v5, v1
	v_mul_lo_u32 v3, v1, v2
	v_sub_u32_e32 v3, v5, v3
	v_add_u32_e32 v4, 1, v1
	v_cmp_ge_u32_e32 vcc, v3, v2
	s_nop 1
	v_cndmask_b32_e32 v1, v1, v4, vcc
	v_sub_u32_e32 v4, v3, v2
	v_cndmask_b32_e32 v3, v3, v4, vcc
	v_add_u32_e32 v4, 1, v1
	v_cmp_ge_u32_e32 vcc, v3, v2
	v_add_u32_e32 v3, 1, v5
	s_nop 0
	v_cndmask_b32_e32 v1, v1, v4, vcc
	v_mul_lo_u32 v4, v2, v1
	v_add_u32_e32 v2, v4, v2
	v_cmp_ne_u32_e32 vcc, v3, v2
	s_and_saveexec_b64 s[8:9], vcc
	s_xor_b64 s[8:9], exec, s[8:9]
	s_cbranch_execz .LBB0_163
	s_waitcnt lgkmcnt(0)
	v_add_u32_e32 v4, 1, v1
	v_mul_lo_u32 v4, v4, v0
	v_mov_b32_e32 v5, 0x2303000
	v_mov_b32_e32 v0, 0x2000
	global_load_dword v0, v5, s[70:71] offset:1024 sc1
	s_add_u32 s18, s6, 0x2400
	s_addc_u32 s19, s7, 0
	s_waitcnt vmcnt(0)
	v_cmp_lt_u32_e32 vcc, v0, v4
	s_and_saveexec_b64 s[10:11], vcc
	s_cbranch_execz .LBB0_162
	s_add_u32 s12, s70, 0x2300200
	s_addc_u32 s13, s71, 0
	s_mov_b32 s14, 1
	s_mov_b64 s[20:21], 0
	v_mov_b32_e32 v0, 0
	s_branch .LBB0_153

; __device__ __forceinline__ unsigned xb_ld(unsigned* p)              { return __hip_atomic_load(p, __ATOMIC_RELAXED, __HIP_MEMORY_SCOPE_AGENT); }
; __device__ __forceinline__ unsigned xb_add(unsigned* p, unsigned v) { return __hip_atomic_fetch_add(p, v, __ATOMIC_RELAXED, __HIP_MEMORY_SCOPE_AGENT); }
; #define XB_SPIN(cond, bar) do { unsigned _sp = 0; while (cond) { __builtin_amdgcn_s_sleep(1); \
;     if ((++_sp & 255u) == 0u) { if (xb_ld(&(bar)[XB_TMO])) break; if (_sp > XB_SPIN_CAP) { atomicAdd(&(bar)[XB_TMO], 1u); break; } } } } while (0)
; __device__ __forceinline__ void xcd_barrier(const XcdBarrier& b) {
;     ...
;         const unsigned old = xb_add(&bar[XB_XSUB(b.x)], 1u);
;         const unsigned gen = old / nloc;
;         if (old + 1u == (gen + 1u) * nloc) {
;             __builtin_amdgcn_fence(__ATOMIC_RELEASE, "agent");
;             asm volatile("s_waitcnt vmcnt(0)" ::: "memory");
;             const unsigned og = xb_add(&bar[XB_TOP], 1u);
;             const unsigned tg = og / nx;
;             if (og + 1u == (tg + 1u) * nx) xb_add(&bar[XB_TOPGEN], 1u);
;             else XB_SPIN(xb_ld(&bar[XB_TOPGEN]) == tg, bar);
;             __builtin_amdgcn_fence(__ATOMIC_ACQUIRE, "agent");
;             xb_add(&bar[XB_XGEN(b.x)], 1u);
;             asm volatile("s_waitcnt vmcnt(0)" ::: "memory");
;         } else {
;             XB_SPIN(xb_ld(&bar[XB_XGEN(b.x)]) == gen, bar);
;             __builtin_amdgcn_fence(__ATOMIC_ACQUIRE, "agent");
.LBB0_242:
	s_or_b64 exec, exec, s[8:9]
	buffer_inv sc1
	v_cvt_f32_u32_e32 v4, v2
	s_waitcnt vmcnt(1)
	v_readfirstlane_b32 s6, v3
	v_sub_u32_e32 v3, 0, v2
	v_rcp_iflag_f32_e32 v4, v4
	v_add_u32_e32 v5, s6, v1
	v_mul_f32_e32 v4, 0x4f7ffffe, v4
	v_cvt_u32_f32_e32 v4, v4
	v_mul_lo_u32 v1, v3, v4
	v_mul_hi_u32 v1, v4, v1
	v_add_u32_e32 v1, v4, v1
	v_mul_hi_u32 v1, v5, v1
	v_mul_lo_u32 v3, v1, v2
	v_sub_u32_e32 v3, v5, v3
	v_add_u32_e32 v4, 1, v1
	v_cmp_ge_u32_e32 vcc, v3, v2
	s_nop 1
	v_cndmask_b32_e32 v1, v1, v4, vcc
	v_sub_u32_e32 v4, v3, v2
	v_cndmask_b32_e32 v3, v3, v4, vcc
	v_add_u32_e32 v4, 1, v1
	v_cmp_ge_u32_e32 vcc, v3, v2
	v_add_u32_e32 v3, 1, v5
	s_nop 0
	v_cndmask_b32_e32 v1, v1, v4, vcc
	v_mul_lo_u32 v4, v2, v1
	v_add_u32_e32 v2, v4, v2
	v_cmp_ne_u32_e32 vcc, v3, v2
	s_and_saveexec_b64 s[6:7], vcc
	s_xor_b64 s[6:7], exec, s[6:7]
	s_cbranch_execz .LBB0_256
	s_waitcnt lgkmcnt(0)
	v_add_u32_e32 v4, 1, v1
	v_mul_lo_u32 v4, v4, v0
	v_mov_b32_e32 v5, 0x2303000
	v_mov_b32_e32 v0, 0x2000
	global_load_dword v0, v5, s[70:71] offset:1024 sc1
	s_add_u32 s12, s4, 0x2400
	s_addc_u32 s13, s5, 0
	s_waitcnt vmcnt(0)
	v_cmp_lt_u32_e32 vcc, v0, v4
	s_and_saveexec_b64 s[8:9], vcc
	s_cbranch_execz .LBB0_255
	s_add_u32 s10, s70, 0x2300200
	s_addc_u32 s11, s71, 0
	s_mov_b32 s14, 1
	s_mov_b64 s[18:19], 0
	v_mov_b32_e32 v0, 0
	s_branch .LBB0_246

; __device__ __forceinline__ unsigned xb_ld(unsigned* p)              { return __hip_atomic_load(p, __ATOMIC_RELAXED, __HIP_MEMORY_SCOPE_AGENT); }
; __device__ __forceinline__ unsigned xb_add(unsigned* p, unsigned v) { return __hip_atomic_fetch_add(p, v, __ATOMIC_RELAXED, __HIP_MEMORY_SCOPE_AGENT); }
; #define XB_SPIN(cond, bar) do { unsigned _sp = 0; while (cond) { __builtin_amdgcn_s_sleep(1); \
;     if ((++_sp & 255u) == 0u) { if (xb_ld(&(bar)[XB_TMO])) break; if (_sp > XB_SPIN_CAP) { atomicAdd(&(bar)[XB_TMO], 1u); break; } } } } while (0)
; __device__ __forceinline__ void xcd_barrier(const XcdBarrier& b) {
;     ...
;         const unsigned old = xb_add(&bar[XB_XSUB(b.x)], 1u);
;         const unsigned gen = old / nloc;
;         if (old + 1u == (gen + 1u) * nloc) {
;             __builtin_amdgcn_fence(__ATOMIC_RELEASE, "agent");
;             asm volatile("s_waitcnt vmcnt(0)" ::: "memory");
;             const unsigned og = xb_add(&bar[XB_TOP], 1u);
;             const unsigned tg = og / nx;
;             if (og + 1u == (tg + 1u) * nx) xb_add(&bar[XB_TOPGEN], 1u);
;             else XB_SPIN(xb_ld(&bar[XB_TOPGEN]) == tg, bar);
;             __builtin_amdgcn_fence(__ATOMIC_ACQUIRE, "agent");
;             xb_add(&bar[XB_XGEN(b.x)], 1u);
;             asm volatile("s_waitcnt vmcnt(0)" ::: "memory");
;         } else {
;             XB_SPIN(xb_ld(&bar[XB_XGEN(b.x)]) == gen, bar);
;             __builtin_amdgcn_fence(__ATOMIC_ACQUIRE, "agent");
.LBB0_785:
	s_or_b64 exec, exec, s[10:11]
	buffer_inv sc1
	v_cvt_f32_u32_e32 v4, v2
	s_waitcnt vmcnt(1)
	v_readfirstlane_b32 s3, v3
	v_sub_u32_e32 v3, 0, v2
	v_rcp_iflag_f32_e32 v4, v4
	v_add_u32_e32 v5, s3, v1
	v_mul_f32_e32 v4, 0x4f7ffffe, v4
	v_cvt_u32_f32_e32 v4, v4
	v_mul_lo_u32 v1, v3, v4
	v_mul_hi_u32 v1, v4, v1
	v_add_u32_e32 v1, v4, v1
	v_mul_hi_u32 v1, v5, v1
	v_mul_lo_u32 v3, v1, v2
	v_sub_u32_e32 v3, v5, v3
	v_add_u32_e32 v4, 1, v1
	v_cmp_ge_u32_e32 vcc, v3, v2
	s_nop 1
	v_cndmask_b32_e32 v1, v1, v4, vcc
	v_sub_u32_e32 v4, v3, v2
	v_cndmask_b32_e32 v3, v3, v4, vcc
	v_add_u32_e32 v4, 1, v1
	v_cmp_ge_u32_e32 vcc, v3, v2
	v_add_u32_e32 v3, 1, v5
	s_nop 0
	v_cndmask_b32_e32 v1, v1, v4, vcc
	v_mul_lo_u32 v4, v2, v1
	v_add_u32_e32 v2, v4, v2
	v_cmp_ne_u32_e32 vcc, v3, v2
	s_and_saveexec_b64 s[8:9], vcc
	s_xor_b64 s[8:9], exec, s[8:9]
	s_cbranch_execz .LBB0_799
	s_waitcnt lgkmcnt(0)
	v_add_u32_e32 v4, 1, v1
	v_mul_lo_u32 v4, v4, v0
	v_mov_b32_e32 v5, 0x2303000
	v_mov_b32_e32 v0, 0x2000
	global_load_dword v0, v5, s[70:71] offset:1024 sc1
	s_add_u32 s14, s6, 0x2400
	s_addc_u32 s15, s7, 0
	s_waitcnt vmcnt(0)
	v_cmp_lt_u32_e32 vcc, v0, v4
	s_and_saveexec_b64 s[10:11], vcc
	s_cbranch_execz .LBB0_798
	s_add_u32 s12, s70, 0x2300200
	s_addc_u32 s13, s71, 0
	s_mov_b32 s3, 1
	s_mov_b64 s[18:19], 0
	v_mov_b32_e32 v0, 0
	s_branch .LBB0_789
